# GLA scan steady-state step: 15 v_pk_mul_f32 (state decay) between MFMAs split into scalar v_mul_f32 pairs (packed-f32-beside-MFMA anti-lever)
# baseline (speedup 1.0000x reference)
; DI void phase_scan(int wid0, const Params& p, unsigned char* lds, bool dry) {
;     ...
;             const unsigned vao = vs_base + (unsigned)(cur * 9216 + (8 * l4 + (l15 >> 2)) * 144 + 2 * (16 * cb0 + 4 * (l15 & 3)));
;             const unsigned vau = vs_base + (unsigned)(cur * 9216 + (8 * hi + (l15 >> 2)) * 144 + 2 * (16 * ((lane >> 4) & 1) + 4 * (l15 & 3)));
;             s16x4 ol[2][2], oh[2][2], ul0[4], uh0[4], ul1[4], uh1[4];
; #pragma unroll
;             for (int cc = 0; cc < 2; ++cc)
; #pragma unroll
;                 for (int s = 0; s < 2; ++s) { ol[cc][s] = tr_read0(vao + cc * 32 + s * 32 * 144); oh[cc][s] = tr_read0(vao + cc * 32 + s * 32 * 144 + 4 * 144); }
; #pragma unroll
;             for (int s = 0; s < 2; ++s) {
;                 ul0[s] = tr_read0(vau + s * 16 * 144); uh0[s] = tr_read0(vau + s * 16 * 144 + 4 * 144);
;                 ul1[s] = tr_read0(vau + s * 16 * 144 + 64); uh1[s] = tr_read0(vau + s * 16 * 144 + 4 * 144 + 64);
;             }
;             {
;                 __builtin_amdgcn_sched_barrier(0);
;                 f32x4 oacc[2];
; #pragma unroll
;                 for (int cc = 0; cc < 2; ++cc) {
;                     const int cb = cb0 + cc; oacc[cc] = (f32x4){0.f, 0.f, 0.f, 0.f};
; #pragma unroll
;                     for (int s = 0; s < 2; ++s) oacc[cc] = MFMA16(PK8(ol[cc][s], oh[cc][s]), at[s], oacc[cc]);
;                     const bf16_t* sp = sbt + cur * 16896 + (16 * cb + l15) * 264 + 8 * l4;
; #pragma unroll
;                     for (int s = 0; s < 8; ++s) { const bf16x8 bfr = *(const bf16x8*)(sp + 32 * s); oacc[cc] = MFMA16(bfr, aq[s], oacc[cc]); }
;                 }
; #pragma unroll
;                 for (int s = 2; s < 4; ++s) {
;                     ul0[s] = tr_read0(vau + s * 16 * 144); uh0[s] = tr_read0(vau + s * 16 * 144 + 4 * 144);
;                     ul1[s] = tr_read0(vau + s * 16 * 144 + 64); uh1[s] = tr_read0(vau + s * 16 * 144 + 4 * 144 + 64);
;                 }
; #pragma unroll
;                 for (int cc = 0; cc < 2; ++cc) {
;                     const int col = colv + 16 * (cb0 + cc) + 4 * l4;
;                     u32x2 w; w.x = cvt_pk_bf16(oacc[cc][0], oacc[cc][1]); w.y = cvt_pk_bf16(oacc[cc][2], oacc[cc][3]);
;                     if (dry) {} else if (c > 0) *(u32x2*)(vb + (size_t)(row0 + i) * 2048 + col) = w;
.LBB0_239:
	v_add_u32_e32 v62, s9, v181
	v_add_u32_e32 v179, s9, v180
	ds_read_b64_tr_b16 v[198:199], v62 offset:576
	ds_read_b64_tr_b16 v[196:197], v62
	ds_read_b64_tr_b16 v[202:203], v62 offset:608
	ds_read_b64_tr_b16 v[200:201], v62 offset:32
	ds_read_b64_tr_b16 v[204:205], v62 offset:4608
	ds_read_b64_tr_b16 v[206:207], v62 offset:5184
	ds_read_b64_tr_b16 v[210:211], v62 offset:5216
	ds_read_b64_tr_b16 v[208:209], v62 offset:4640
	ds_read_b64_tr_b16 v[82:83], v179
	ds_read_b64_tr_b16 v[84:85], v179 offset:576
	ds_read_b64_tr_b16 v[80:81], v179 offset:640
	ds_read_b64_tr_b16 v[78:79], v179 offset:64
	ds_read_b64_tr_b16 v[74:75], v179 offset:2304
	ds_read_b64_tr_b16 v[76:77], v179 offset:2880
	ds_read_b64_tr_b16 v[64:65], v179 offset:2944
	ds_read_b64_tr_b16 v[62:63], v179 offset:2368
	s_waitcnt vmcnt(17) lgkmcnt(14)
	v_mfma_f32_16x16x32_bf16 v[196:199], v[196:199], v[118:121], 0
	s_mul_i32 s9, s7, 0x8400
	v_add_u32_e32 v212, s9, v182
	v_add_u32_e32 v213, v212, v145
	s_waitcnt lgkmcnt(12)
	v_mfma_f32_16x16x32_bf16 v[118:121], v[200:203], v[118:121], 0
	v_add_u32_e32 v200, v212, v189
	s_waitcnt vmcnt(0)
	v_mul_f32_e32 v32, v32, v72
	v_mul_f32_e32 v33, v33, v73
	v_mul_f32_e32 v28, v28, v60
	v_mul_f32_e32 v29, v29, v61
	s_waitcnt lgkmcnt(10)
	v_mfma_f32_16x16x32_bf16 v[196:199], v[204:207], v[122:125], v[196:199]
	ds_read_b128 v[214:217], v213
	v_mul_f32_e32 v24, v24, v56
	v_mul_f32_e32 v25, v25, v57
	v_mul_f32_e32 v20, v20, v68
	v_mul_f32_e32 v21, v21, v69
	s_waitcnt lgkmcnt(9)
	v_mfma_f32_16x16x32_bf16 v[118:121], v[208:211], v[122:125], v[118:121]
	ds_read_b128 v[218:221], v200
	v_mul_f32_e32 v18, v18, v66
	v_mul_f32_e32 v19, v19, v67
	v_mul_f32_e32 v30, v30, v70
	v_mul_f32_e32 v31, v31, v71
	ds_read_b128 v[222:225], v213 offset:64
	ds_read_b128 v[226:229], v200 offset:64
	s_waitcnt lgkmcnt(3)
	v_mfma_f32_16x16x32_bf16 v[196:199], v[214:217], v[114:117], v[196:199]
	v_mul_f32_e32 v26, v26, v58
	v_mul_f32_e32 v27, v27, v59
	v_mul_f32_e32 v22, v22, v54
	v_mul_f32_e32 v23, v23, v55
	ds_read_b128 v[236:239], v213 offset:128
	s_waitcnt lgkmcnt(3)
	v_mfma_f32_16x16x32_bf16 v[114:117], v[218:221], v[114:117], v[118:121]
	v_mul_f32_e64 v16, v16, v72
	v_mul_f32_e64 v17, v17, v73
	v_mul_f32_e32 v12, v12, v60
	v_mul_f32_e32 v13, v13, v61
	v_mul_f32_e32 v8, v8, v56
	v_mul_f32_e32 v9, v9, v57
	ds_read_b128 v[240:243], v200 offset:128
	s_waitcnt lgkmcnt(3)
	v_mfma_f32_16x16x32_bf16 v[196:199], v[222:225], v[98:101], v[196:199]
	v_mul_f32_e32 v4, v4, v68
	v_mul_f32_e32 v5, v5, v69
	v_mul_f32_e32 v2, v2, v66
	v_mul_f32_e32 v3, v3, v67
	ds_read_b128 v[248:251], v213 offset:192
	s_waitcnt lgkmcnt(3)
	v_mfma_f32_16x16x32_bf16 v[98:101], v[226:229], v[98:101], v[114:117]
	s_nop 2
	v_mul_f32_e32 v14, v14, v70
	v_mul_f32_e32 v15, v15, v71
	v_mul_f32_e32 v10, v10, v58
	v_mul_f32_e32 v11, v11, v59
	ds_read_b128 v[252:255], v200 offset:192
	s_waitcnt lgkmcnt(3)
	v_mfma_f32_16x16x32_bf16 v[196:199], v[236:239], v[110:113], v[196:199]
	v_mul_f32_e32 v6, v6, v54
	v_mul_f32_e32 v7, v7, v55
	ds_read_b128 v[214:217], v213 offset:256
	s_waitcnt lgkmcnt(3)
	v_mfma_f32_16x16x32_bf16 v[98:101], v[240:243], v[110:113], v[98:101]
	ds_read_b128 v[218:221], v200 offset:256
	s_waitcnt lgkmcnt(3)
	v_mfma_f32_16x16x32_bf16 v[196:199], v[248:251], v[86:89], v[196:199]
	ds_read_b128 v[222:225], v213 offset:320
	s_waitcnt lgkmcnt(3)
	v_mfma_f32_16x16x32_bf16 v[86:89], v[252:255], v[86:89], v[98:101]
	s_nop 2
	ds_read_b128 v[226:229], v200 offset:320
	s_waitcnt lgkmcnt(3)
	v_mfma_f32_16x16x32_bf16 v[196:199], v[214:217], v[102:105], v[196:199]
	ds_read_b128 v[236:239], v213 offset:384
	s_waitcnt lgkmcnt(3)
	v_mfma_f32_16x16x32_bf16 v[86:89], v[218:221], v[102:105], v[86:89]
	ds_read_b128 v[240:243], v200 offset:384
	s_waitcnt lgkmcnt(3)
	v_mfma_f32_16x16x32_bf16 v[196:199], v[222:225], v[90:93], v[196:199]
	ds_read_b128 v[248:251], v213 offset:448
	s_waitcnt lgkmcnt(3)
	v_mfma_f32_16x16x32_bf16 v[86:89], v[226:229], v[90:93], v[86:89]
	ds_read_b128 v[252:255], v200 offset:448
	s_waitcnt lgkmcnt(3)
	v_mfma_f32_16x16x32_bf16 v[196:199], v[236:239], v[106:109], v[196:199]
	s_waitcnt lgkmcnt(2)
	v_mfma_f32_16x16x32_bf16 v[86:89], v[240:243], v[106:109], v[86:89]
	v_add_u32_e32 v106, s8, v194
	v_ashrrev_i32_e32 v107, 31, v106
	s_waitcnt lgkmcnt(1)
	v_mfma_f32_16x16x32_bf16 v[196:199], v[248:251], v[94:97], v[196:199]
	v_lshlrev_b64 v[106:107], 12, v[106:107]
	v_lshl_add_u64 v[106:107], s[28:29], 0, v[106:107]
	v_lshl_add_u64 v[110:111], v[106:107], 0, v[0:1]
	s_waitcnt lgkmcnt(0)
	v_mfma_f32_16x16x32_bf16 v[86:89], v[252:255], v[94:97], v[86:89]
	ds_read_b64_tr_b16 v[90:91], v179 offset:4608
	ds_read_b64_tr_b16 v[92:93], v179 offset:5184
	ds_read_b64_tr_b16 v[94:95], v179 offset:4672
	ds_read_b64_tr_b16 v[96:97], v179 offset:5248
	ds_read_b64_tr_b16 v[98:99], v179 offset:6912
	ds_read_b64_tr_b16 v[100:101], v179 offset:7488
	ds_read_b64_tr_b16 v[102:103], v179 offset:6976
	ds_read_b64_tr_b16 v[104:105], v179 offset:7552
	v_mov_b32_e32 v179, v1
	v_cvt_pk_bf16_f32 v108, v196, v197
	v_cvt_pk_bf16_f32 v109, v198, v199
	v_cvt_pk_bf16_f32 v86, v86, v87
	v_cvt_pk_bf16_f32 v87, v88, v89
	v_lshl_add_u64 v[88:89], v[106:107], 0, v[178:179]
	global_store_dwordx2 v[110:111], v[108:109], off
	global_store_dwordx2 v[88:89], v[86:87], off
	v_mfma_f32_32x32x16_bf16 v[18:33], v[50:53], v[82:85], v[18:33]
	s_xor_b32 s7, s7, 1
	s_mul_i32 s7, s7, 0x8400
	s_add_i32 s8, s8, 64
	s_add_i32 s6, s6, 4
	s_add_i32 s2, s2, 1
	s_cmpk_eq_i32 s8, 0x1000
	v_mfma_f32_32x32x16_bf16 v[2:17], v[50:53], v[78:81], v[2:17]
	v_mfma_f32_32x32x16_bf16 v[18:33], v[46:49], v[74:77], v[18:33]
	v_mfma_f32_32x32x16_bf16 v[2:17], v[46:49], v[62:65], v[2:17]
	v_add_u32_e32 v46, s7, v131
	v_add_u32_e32 v47, 0x4000, v46
	s_waitcnt lgkmcnt(6)
	v_mfma_f32_32x32x16_bf16 v[18:33], v[42:45], v[90:93], v[18:33]
	s_waitcnt lgkmcnt(4)
	v_mfma_f32_32x32x16_bf16 v[2:17], v[42:45], v[94:97], v[2:17]
	s_waitcnt lgkmcnt(2)
	v_mfma_f32_32x32x16_bf16 v[18:33], v[38:41], v[98:101], v[18:33]
	s_waitcnt lgkmcnt(0)
	v_mfma_f32_32x32x16_bf16 v[2:17], v[38:41], v[102:105], v[2:17]
	s_nop 9
	v_cvt_pk_bf16_f32 v42, v18, v19
	v_cvt_pk_bf16_f32 v43, v20, v21
	v_cvt_pk_bf16_f32 v40, v22, v23
	v_cvt_pk_bf16_f32 v41, v24, v25
	ds_write2_b64 v46, v[42:43], v[40:41] offset1:2
	v_cvt_pk_bf16_f32 v42, v30, v31
	v_cvt_pk_bf16_f32 v43, v32, v33
	v_cvt_pk_bf16_f32 v38, v2, v3
	v_cvt_pk_bf16_f32 v39, v4, v5
	v_cvt_pk_bf16_f32 v44, v6, v7
	v_cvt_pk_bf16_f32 v45, v8, v9
	ds_write2_b64 v47, v[38:39], v[44:45] offset0:64 offset1:66
	v_cvt_pk_bf16_f32 v38, v26, v27
	v_cvt_pk_bf16_f32 v39, v28, v29
	v_cvt_pk_bf16_f32 v40, v10, v11
	v_cvt_pk_bf16_f32 v41, v12, v13
	v_cvt_pk_bf16_f32 v44, v14, v15
	v_cvt_pk_bf16_f32 v45, v16, v17
	ds_write2_b64 v46, v[38:39], v[42:43] offset0:4 offset1:6
	ds_write2_b64 v47, v[40:41], v[44:45] offset0:68 offset1:70
	s_cbranch_scc1 .LBB0_228
